# E50: E48 plus PH9 LayerNorm epilogue pass-2 parameter loads issued before the LDS exchange reads and barrier; PH11 owner slab poll s_sleep 8 -> 1
# speedup vs baseline: 1.0020x; 1.0020x over previous
.LBB0_2472:
	s_or_b64 exec, exec, s[4:5]
	s_waitcnt lgkmcnt(0)
	s_barrier
	v_mbcnt_lo_u32_b32 v0, -1, 0
	v_mbcnt_hi_u32_b32 v0, -1, v0
	s_mulk_i32 s10, 0xd00
	v_and_b32_e32 v1, 15, v0
	v_ashrrev_i32_e32 v2, 1, v0
	v_or_b32_e32 v79, s24, v1
	v_and_b32_e32 v117, -8, v2
	s_add_i32 s6, s10, 0
	v_lshl_add_u32 v2, v79, 4, 0
	v_add_u32_e32 v187, s75, v117
	s_add_i32 s6, s6, 0x20000
	s_add_i32 s12, s24, s23
	v_add_u32_e32 v2, 0x26000, v2
	v_mov_b32_e32 v28, v187
	s_add_u32 s80, s90, s18
	s_addc_u32 s81, s91, s19
	v_ashrrev_i32_e32 v29, 31, v28
	v_lshlrev_b64 v[28:29], 2, v[28:29]
	s_add_u32 s82, s90, s16
	v_readlane_b32 s40, v255, 19
	v_lshl_add_u64 v[30:31], s[80:81], 0, v[28:29]
	s_addc_u32 s83, s91, s17
	v_readlane_b32 s46, v255, 25
	v_readlane_b32 s47, v255, 26
	v_readlane_b32 s48, v255, 27
	v_readlane_b32 s49, v255, 28
	v_lshl_add_u64 v[32:33], s[82:83], 0, v[28:29]
	v_lshl_add_u64 v[34:35], s[46:47], 0, v[28:29]
	v_lshl_add_u64 v[126:127], s[48:49], 0, v[28:29]
	v_add_co_u32_e32 v28, vcc, s38, v30
	global_load_dwordx4 v[52:55], v[34:35], off
	global_load_dwordx4 v[56:59], v[126:127], off
	global_load_dwordx4 v[60:63], v[30:31], off
	v_addc_co_u32_e32 v29, vcc, 0, v31, vcc
	v_add_co_u32_e32 v36, vcc, s38, v32
	global_load_dwordx4 v[64:67], v[32:33], off
	s_nop 0
	v_addc_co_u32_e32 v37, vcc, 0, v33, vcc
	global_load_dwordx4 v[68:71], v[28:29], off
	global_load_dwordx4 v[72:75], v[36:37], off
	s_nop 0
	global_load_dwordx4 v[36:39], v[30:31], off offset:16
	global_load_dwordx4 v[44:47], v[32:33], off offset:16
	v_lshl_add_u64 v[28:29], v[30:31], 0, s[72:73]
	v_lshl_add_u64 v[30:31], v[32:33], 0, s[72:73]
	global_load_dwordx4 v[40:43], v[28:29], off offset:16
	global_load_dwordx4 v[48:51], v[30:31], off offset:16
	s_nop 0
	global_load_dwordx4 v[28:31], v[34:35], off offset:16
	s_nop 0
	global_load_dwordx4 v[32:35], v[126:127], off offset:16
	ds_read_b128 v[24:27], v2
	ds_read_b128 v[20:23], v2 offset:256
	ds_read_b128 v[16:19], v2 offset:512
	s_waitcnt lgkmcnt(3)
	ds_read_b128 v[12:15], v2 offset:1536
	ds_read_b128 v[8:11], v2 offset:1792
	ds_read_b128 v[4:7], v2 offset:2048
	s_waitcnt lgkmcnt(0)
	s_barrier
	v_add_u32_e32 v140, s23, v79
	v_mul_lo_u32 v79, v117, s63
	v_add_u32_e32 v127, s6, v79
	s_waitcnt lgkmcnt(5)
	v_sub_f32_e32 v79, v168, v24
	v_sub_f32_e32 v78, v78, v24
	v_sub_f32_e32 v151, v164, v24
	v_sub_f32_e32 v150, v166, v24
	v_pk_mul_f32 v[78:79], v[24:25], v[78:79] op_sel:[1,0]
	v_and_b32_e32 v141, 1, v0
	v_pk_mul_f32 v[150:151], v[24:25], v[150:151] op_sel:[1,0]
	v_cmp_gt_i32_e64 s[24:25], s15, v140
	v_sub_f32_e32 v77, v77, v24
	v_sub_f32_e32 v76, v76, v24
	v_lshlrev_b32_e32 v153, 4, v141
	v_mov_b32_e32 v152, v27
	v_sub_f32_e32 v163, v169, v24
	v_sub_f32_e32 v162, v167, v24
	v_pk_mul_f32 v[76:77], v[24:25], v[76:77] op_sel:[1,0]
	v_lshlrev_b32_e32 v2, 3, v0
	v_bfe_u32 v126, v0, 1, 3
	v_pk_mul_f32 v[162:163], v[24:25], v[162:163] op_sel:[1,0]
	s_movk_i32 s0, 0xfff
	v_and_or_b32 v126, v2, 8, v126
	v_cmp_lt_i32_e32 vcc, s0, v140
	s_waitcnt lgkmcnt(4)
	v_sub_f32_e32 v165, v171, v20
	v_sub_f32_e32 v164, v170, v20
	v_cndmask_b32_e32 v117, v1, v126, vcc
	v_lshlrev_b32_e32 v117, 1, v117
	v_pk_mul_f32 v[164:165], v[20:21], v[164:165] op_sel:[1,0]
	s_movk_i32 s0, 0xfef
	v_cmp_lt_i32_e64 s[0:1], s0, v140
	v_lshlrev_b32_e32 v2, 3, v141
	v_readlane_b32 s41, v255, 20
	v_readlane_b32 s42, v255, 21
	v_readlane_b32 s43, v255, 22
	v_readlane_b32 s44, v255, 23
	v_readlane_b32 s45, v255, 24
	v_readlane_b32 s50, v255, 29
	v_readlane_b32 s51, v255, 30
	v_readlane_b32 s52, v255, 31
	v_readlane_b32 s53, v255, 32
	v_readlane_b32 s54, v255, 33
	v_readlane_b32 s55, v255, 34
	s_waitcnt vmcnt(10)
	v_pk_fma_f32 v[78:79], v[78:79], v[54:55], v[58:59]
	v_pk_fma_f32 v[150:151], v[150:151], v[52:53], v[56:57]
	v_sub_f32_e32 v79, v79, v26
	v_sub_f32_e32 v78, v78, v26
	v_sub_f32_e32 v151, v151, v26
	v_sub_f32_e32 v150, v150, v26
	s_waitcnt vmcnt(8)
	v_cndmask_b32_e64 v157, v67, v63, s[24:25]
	s_waitcnt vmcnt(6)
	v_cndmask_b32_e64 v159, v75, v71, s[24:25]
	v_cndmask_b32_e64 v158, v74, v70, s[24:25]
	v_cndmask_b32_e64 v156, v66, v62, s[24:25]
	v_cndmask_b32_e64 v161, v73, v69, s[24:25]
	v_cndmask_b32_e64 v160, v72, v68, s[24:25]
	v_pk_mul_f32 v[78:79], v[152:153], v[78:79] op_sel_hi:[0,1]
	v_pk_add_f32 v[158:159], v[158:159], 1.0 op_sel_hi:[1,0]
	s_waitcnt vmcnt(0)
	v_pk_fma_f32 v[76:77], v[76:77], v[30:31], v[34:35]
	v_cndmask_b32_e64 v155, v65, v61, s[24:25]
	v_cndmask_b32_e64 v154, v64, v60, s[24:25]
	v_pk_mul_f32 v[150:151], v[152:153], v[150:151] op_sel_hi:[0,1]
	v_pk_add_f32 v[160:161], v[160:161], 1.0 op_sel_hi:[1,0]
	v_pk_fma_f32 v[78:79], v[78:79], v[158:159], v[156:157]
	v_cndmask_b32_e64 v159, v51, v43, s[24:25]
	v_cndmask_b32_e64 v158, v50, v42, s[24:25]
	v_pk_fma_f32 v[162:163], v[162:163], v[28:29], v[32:33]
	v_sub_f32_e32 v77, v77, v26
	v_sub_f32_e32 v76, v76, v26
	v_pk_fma_f32 v[150:151], v[150:151], v[160:161], v[154:155]
	v_cndmask_b32_e64 v157, v47, v39, s[24:25]
	v_cndmask_b32_e64 v156, v46, v38, s[24:25]
	v_cndmask_b32_e64 v161, v49, v41, s[24:25]
	v_cndmask_b32_e64 v160, v48, v40, s[24:25]
	v_sub_f32_e32 v163, v163, v26
	v_sub_f32_e32 v162, v162, v26
	v_pk_mul_f32 v[76:77], v[152:153], v[76:77] op_sel_hi:[0,1]
	v_pk_add_f32 v[158:159], v[158:159], 1.0 op_sel_hi:[1,0]
	v_cndmask_b32_e64 v155, v45, v37, s[24:25]
	v_cndmask_b32_e64 v154, v44, v36, s[24:25]
	v_pk_mul_f32 v[162:163], v[152:153], v[162:163] op_sel_hi:[0,1]
	v_pk_add_f32 v[160:161], v[160:161], 1.0 op_sel_hi:[1,0]
	v_pk_fma_f32 v[76:77], v[76:77], v[158:159], v[156:157]
	v_pk_fma_f32 v[156:157], v[162:163], v[160:161], v[154:155]
	v_add_u32_e32 v154, v127, v117
	v_cvt_pk_bf16_f32 v117, v150, v151
	v_cvt_pk_bf16_f32 v78, v78, v79
	v_cvt_pk_bf16_f32 v79, v156, v157
	v_cvt_pk_bf16_f32 v76, v76, v77
	v_sub_f32_e32 v159, v174, v20
	v_sub_f32_e32 v158, v176, v20
	ds_write_b16 v154, v117
	ds_write_b16_d16_hi v154, v117 offset:104
	ds_write_b16 v154, v78 offset:208
	ds_write_b16_d16_hi v154, v78 offset:312
	ds_write_b16 v154, v79 offset:416
	ds_write_b16_d16_hi v154, v79 offset:520
	ds_write_b16 v154, v76 offset:624
	ds_write_b16_d16_hi v154, v76 offset:728
	v_add_u32_e32 v76, 16, v140
	v_sub_f32_e32 v161, v178, v20
	v_sub_f32_e32 v160, v172, v20
	v_pk_mul_f32 v[158:159], v[20:21], v[158:159] op_sel:[1,0]
	v_cmp_gt_i32_e32 vcc, s15, v76
	v_pk_mul_f32 v[160:161], v[20:21], v[160:161] op_sel:[1,0]
	v_pk_fma_f32 v[158:159], v[158:159], v[52:53], v[56:57]
	v_cndmask_b32_e32 v157, v73, v69, vcc
	v_cndmask_b32_e32 v156, v72, v68, vcc
	v_pk_fma_f32 v[160:161], v[160:161], v[54:55], v[58:59]
	v_sub_f32_e32 v159, v159, v22
	v_sub_f32_e32 v158, v158, v22
	v_mov_b32_e32 v152, v23
	v_sub_f32_e32 v163, v179, v20
	v_sub_f32_e32 v162, v177, v20
	v_cndmask_b32_e32 v77, v65, v61, vcc
	v_cndmask_b32_e32 v76, v64, v60, vcc
	v_cndmask_b32_e32 v151, v75, v71, vcc
	v_cndmask_b32_e32 v150, v74, v70, vcc
	v_sub_f32_e32 v161, v161, v22
	v_sub_f32_e32 v160, v160, v22
	v_pk_mul_f32 v[158:159], v[152:153], v[158:159] op_sel_hi:[0,1]
	v_pk_add_f32 v[156:157], v[156:157], 1.0 op_sel_hi:[1,0]
	v_pk_mul_f32 v[162:163], v[20:21], v[162:163] op_sel:[1,0]
	v_pk_fma_f32 v[164:165], v[164:165], v[30:31], v[34:35]
	v_cndmask_b32_e32 v79, v67, v63, vcc
	v_cndmask_b32_e32 v78, v66, v62, vcc
	v_pk_mul_f32 v[160:161], v[152:153], v[160:161] op_sel_hi:[0,1]
	v_pk_add_f32 v[150:151], v[150:151], 1.0 op_sel_hi:[1,0]
	v_pk_fma_f32 v[76:77], v[158:159], v[156:157], v[76:77]
	v_cndmask_b32_e32 v159, v51, v43, vcc
	v_cndmask_b32_e32 v158, v50, v42, vcc
	v_pk_fma_f32 v[162:163], v[162:163], v[28:29], v[32:33]
	v_sub_f32_e32 v165, v165, v22
	v_sub_f32_e32 v164, v164, v22
	v_cndmask_b32_e64 v117, v1, v126, s[0:1]
	v_pk_fma_f32 v[78:79], v[160:161], v[150:151], v[78:79]
	v_cndmask_b32_e32 v157, v47, v39, vcc
	v_cndmask_b32_e32 v156, v46, v38, vcc
	v_cndmask_b32_e32 v161, v49, v41, vcc
	v_cndmask_b32_e32 v160, v48, v40, vcc
	v_sub_f32_e32 v163, v163, v22
	v_sub_f32_e32 v162, v162, v22
	v_pk_mul_f32 v[164:165], v[152:153], v[164:165] op_sel_hi:[0,1]
	v_pk_add_f32 v[158:159], v[158:159], 1.0 op_sel_hi:[1,0]
	v_lshlrev_b32_e32 v117, 1, v117
	v_cndmask_b32_e32 v151, v45, v37, vcc
	v_cndmask_b32_e32 v150, v44, v36, vcc
	v_pk_mul_f32 v[162:163], v[152:153], v[162:163] op_sel_hi:[0,1]
	v_pk_add_f32 v[160:161], v[160:161], 1.0 op_sel_hi:[1,0]
	v_pk_fma_f32 v[156:157], v[164:165], v[158:159], v[156:157]
	v_add_u32_e32 v155, v127, v117
	v_cvt_pk_bf16_f32 v76, v76, v77
	s_waitcnt lgkmcnt(11)
	v_sub_f32_e32 v159, v186, v16
	v_sub_f32_e32 v158, v192, v16
	v_pk_fma_f32 v[150:151], v[162:163], v[160:161], v[150:151]
	v_cvt_pk_bf16_f32 v77, v78, v79
	v_sub_f32_e32 v161, v196, v16
	v_cvt_pk_bf16_f32 v78, v150, v151
	v_cvt_pk_bf16_f32 v79, v156, v157
	ds_write_b16 v155, v76 offset:32
	ds_write_b16_d16_hi v155, v76 offset:136
	ds_write_b16 v155, v77 offset:240
	ds_write_b16_d16_hi v155, v77 offset:344
	ds_write_b16 v155, v78 offset:448
	ds_write_b16_d16_hi v155, v78 offset:552
	ds_write_b16 v155, v79 offset:656
	ds_write_b16_d16_hi v155, v79 offset:760
	v_add_u32_e32 v76, 32, v140
	v_sub_f32_e32 v160, v184, v16
	v_pk_mul_f32 v[158:159], v[16:17], v[158:159] op_sel:[1,0]
	v_cmp_gt_i32_e64 s[4:5], s15, v76
	v_pk_mul_f32 v[160:161], v[16:17], v[160:161] op_sel:[1,0]
	v_pk_fma_f32 v[158:159], v[158:159], v[52:53], v[56:57]
	v_sub_f32_e32 v165, v181, v16
	v_sub_f32_e32 v164, v180, v16
	v_cndmask_b32_e64 v157, v73, v69, s[4:5]
	v_cndmask_b32_e64 v156, v72, v68, s[4:5]
	v_pk_fma_f32 v[160:161], v[160:161], v[54:55], v[58:59]
	v_sub_f32_e32 v159, v159, v18
	v_sub_f32_e32 v158, v158, v18
	v_mov_b32_e32 v152, v19
	v_sub_f32_e32 v163, v197, v16
	v_sub_f32_e32 v162, v193, v16
	v_pk_mul_f32 v[164:165], v[16:17], v[164:165] op_sel:[1,0]
	s_movk_i32 s0, 0xfdf
	v_cndmask_b32_e64 v77, v65, v61, s[4:5]
	v_cndmask_b32_e64 v76, v64, v60, s[4:5]
	v_cndmask_b32_e64 v151, v75, v71, s[4:5]
	v_cndmask_b32_e64 v150, v74, v70, s[4:5]
	v_sub_f32_e32 v161, v161, v18
	v_sub_f32_e32 v160, v160, v18
	v_pk_mul_f32 v[158:159], v[152:153], v[158:159] op_sel_hi:[0,1]
	v_pk_add_f32 v[156:157], v[156:157], 1.0 op_sel_hi:[1,0]
	v_pk_mul_f32 v[162:163], v[16:17], v[162:163] op_sel:[1,0]
	v_pk_fma_f32 v[164:165], v[164:165], v[30:31], v[34:35]
	v_cmp_lt_i32_e64 s[0:1], s0, v140
	v_cndmask_b32_e64 v79, v67, v63, s[4:5]
	v_cndmask_b32_e64 v78, v66, v62, s[4:5]
	v_pk_mul_f32 v[160:161], v[152:153], v[160:161] op_sel_hi:[0,1]
	v_pk_add_f32 v[150:151], v[150:151], 1.0 op_sel_hi:[1,0]
	v_pk_fma_f32 v[76:77], v[158:159], v[156:157], v[76:77]
	v_cndmask_b32_e64 v159, v51, v43, s[4:5]
	v_cndmask_b32_e64 v158, v50, v42, s[4:5]
	v_pk_fma_f32 v[162:163], v[162:163], v[28:29], v[32:33]
	v_sub_f32_e32 v165, v165, v18
	v_sub_f32_e32 v164, v164, v18
	v_cndmask_b32_e64 v117, v1, v126, s[0:1]
	v_pk_fma_f32 v[78:79], v[160:161], v[150:151], v[78:79]
	v_cndmask_b32_e64 v157, v47, v39, s[4:5]
	v_cndmask_b32_e64 v156, v46, v38, s[4:5]
	v_cndmask_b32_e64 v161, v49, v41, s[4:5]
	v_cndmask_b32_e64 v160, v48, v40, s[4:5]
	v_sub_f32_e32 v163, v163, v18
	v_sub_f32_e32 v162, v162, v18
	v_pk_mul_f32 v[164:165], v[152:153], v[164:165] op_sel_hi:[0,1]
	v_pk_add_f32 v[158:159], v[158:159], 1.0 op_sel_hi:[1,0]
	v_lshlrev_b32_e32 v117, 1, v117
	v_cndmask_b32_e64 v151, v45, v37, s[4:5]
	v_cndmask_b32_e64 v150, v44, v36, s[4:5]
	v_pk_mul_f32 v[162:163], v[152:153], v[162:163] op_sel_hi:[0,1]
	v_pk_add_f32 v[160:161], v[160:161], 1.0 op_sel_hi:[1,0]
	v_pk_fma_f32 v[158:159], v[164:165], v[158:159], v[156:157]
	v_add_u32_e32 v156, v127, v117
	v_cvt_pk_bf16_f32 v76, v76, v77
	v_pk_fma_f32 v[150:151], v[162:163], v[160:161], v[150:151]
	v_cvt_pk_bf16_f32 v77, v78, v79
	s_nop 0
	v_cvt_pk_bf16_f32 v78, v150, v151
	v_cvt_pk_bf16_f32 v79, v158, v159
	ds_write_b16 v156, v76 offset:64
	ds_write_b16_d16_hi v156, v76 offset:168
	ds_write_b16 v156, v77 offset:272
	ds_write_b16_d16_hi v156, v77 offset:376
	ds_write_b16 v156, v78 offset:480
	ds_write_b16_d16_hi v156, v78 offset:584
	ds_write_b16 v156, v79 offset:688
	ds_write_b16_d16_hi v156, v79 offset:792
	v_mul_hi_i32 v76, v0, s39
	v_lshrrev_b32_e32 v77, 31, v76
	v_add_u32_e32 v164, v76, v77
	v_mad_u64_u32 v[76:77], s[0:1], v164, -6, v[0:1]
	v_ashrrev_i32_e32 v151, 1, v76
	v_mul_lo_u32 v76, v164, s63
	v_lshlrev_b32_e32 v77, 5, v151
	v_add3_u32 v76, s6, v76, v77
	s_waitcnt lgkmcnt(0)
	v_add_u32_e32 v117, v76, v153
	ds_read2_b64 v[76:79], v117 offset1:1
	v_lshlrev_b32_e32 v158, 4, v151
	v_add_u32_e32 v152, s12, v158
	v_lshlrev_b32_e32 v151, 2, v152
	v_add_u32_e32 v150, s75, v164
	v_cmp_gt_i32_e64 s[16:17], s38, v152
	v_and_b32_e32 v167, 0xf0, v152
	v_and_b32_e32 v170, 0xfffc00, v151
	s_and_saveexec_b64 s[0:1], s[16:17]
	s_xor_b64 s[0:1], exec, s[0:1]
	v_add_lshl_u32 v151, v170, v150, 8
	v_or3_b32 v151, v151, v167, v2
	s_or_saveexec_b64 s[0:1], s[0:1]
	v_lshlrev_b32_e32 v141, 11, v141
	v_add_u32_e32 v157, 0x3ff000, v152
	v_lshrrev_b32_e32 v152, 1, v152
	v_lshrrev_b32_e32 v178, 2, v157
	v_and_or_b32 v184, v152, s27, v141
	s_xor_b64 exec, exec, s[0:1]
	v_and_b32_e32 v151, 0xffc00, v178
	v_add_u32_e32 v151, v151, v150
	v_lshl_or_b32 v151, v151, 12, v184
	v_add_u32_e32 v151, 0x400000, v151
	s_or_b64 exec, exec, s[0:1]
	v_lshlrev_b32_e32 v151, 1, v151
	s_waitcnt lgkmcnt(0)
	global_store_dwordx4 v151, v[76:79], s[60:61]
	s_nop 1
	v_add_u32_e32 v76, 64, v0
	v_mul_hi_i32 v77, v76, s39
	v_lshrrev_b32_e32 v78, 31, v77
	v_add_u32_e32 v168, v77, v78
	v_mad_u64_u32 v[76:77], s[0:1], v168, -6, v[76:77]
	v_ashrrev_i32_e32 v157, 1, v76
	v_mul_lo_u32 v76, v168, s63
	v_lshlrev_b32_e32 v77, 5, v157
	v_add3_u32 v76, s6, v76, v77
	v_add_u32_e32 v152, v76, v153
	ds_read2_b64 v[76:79], v152 offset1:1
	v_lshlrev_b32_e32 v159, 4, v157
	v_add_u32_e32 v160, s12, v159
	v_lshlrev_b32_e32 v157, 2, v160
	v_add_u32_e32 v151, s75, v168
	v_cmp_gt_i32_e64 s[18:19], s38, v160
	v_and_b32_e32 v172, 0xf0, v160
	v_and_b32_e32 v174, 0xfffc00, v157
	s_and_saveexec_b64 s[0:1], s[18:19]
	s_xor_b64 s[0:1], exec, s[0:1]
	v_add_lshl_u32 v157, v174, v151, 8
	v_or3_b32 v157, v157, v172, v2
	s_or_saveexec_b64 s[0:1], s[0:1]
	v_add_u32_e32 v161, 0x3ff000, v160
	v_lshrrev_b32_e32 v160, 1, v160
	v_lshrrev_b32_e32 v180, 2, v161
	v_and_or_b32 v185, v160, s27, v141
	s_xor_b64 exec, exec, s[0:1]
	v_and_b32_e32 v157, 0xffc00, v180
	v_add_u32_e32 v157, v157, v151
	v_lshl_or_b32 v157, v157, 12, v185
	v_add_u32_e32 v157, 0x400000, v157
	s_or_b64 exec, exec, s[0:1]
	v_lshlrev_b32_e32 v157, 1, v157
	v_add_u32_e32 v0, 0x80, v0
	s_waitcnt lgkmcnt(0)
	global_store_dwordx4 v157, v[76:79], s[60:61]
	s_nop 1
	v_mul_hi_i32 v76, v0, s39
	v_lshrrev_b32_e32 v77, 31, v76
	v_add_u32_e32 v169, v76, v77
	v_mad_u64_u32 v[76:77], s[0:1], v169, -6, v[0:1]
	v_ashrrev_i32_e32 v157, 1, v76
	v_mul_lo_u32 v0, v169, s63
	v_lshlrev_b32_e32 v76, 5, v157
	v_add3_u32 v0, s6, v0, v76
	v_add_u32_e32 v153, v0, v153
	ds_read2_b64 v[76:79], v153 offset1:1
	v_lshlrev_b32_e32 v162, 4, v157
	v_add_u32_e32 v160, s12, v162
	v_lshlrev_b32_e32 v157, 2, v160
	v_add_u32_e32 v0, s75, v169
	v_cmp_gt_i32_e64 s[20:21], s38, v160
	v_and_b32_e32 v171, 0xf0, v160
	v_and_b32_e32 v173, 0xfffc00, v157
	s_and_saveexec_b64 s[0:1], s[20:21]
	s_xor_b64 s[0:1], exec, s[0:1]
	v_add_lshl_u32 v157, v173, v0, 8
	v_or3_b32 v157, v157, v171, v2
	s_or_saveexec_b64 s[0:1], s[0:1]
	v_add_u32_e32 v161, 0x3ff000, v160
	v_lshrrev_b32_e32 v160, 1, v160
	v_lshrrev_b32_e32 v181, 2, v161
	v_and_or_b32 v186, v160, s27, v141
	s_xor_b64 exec, exec, s[0:1]
	v_and_b32_e32 v157, 0xffc00, v181
	v_add_u32_e32 v157, v157, v0
	v_lshl_or_b32 v157, v157, 12, v186
	v_add_u32_e32 v157, 0x400000, v157
	s_or_b64 exec, exec, s[0:1]
	v_lshlrev_b32_e32 v157, 1, v157
	v_sub_f32_e32 v189, v198, v12
	v_sub_f32_e32 v188, v188, v12
	s_waitcnt lgkmcnt(0)
	global_store_dwordx4 v157, v[76:79], s[60:61]
	v_sub_f32_e32 v191, v190, v12
	v_sub_f32_e32 v190, v194, v12
	v_add_u32_e32 v76, 0x60, v140
	v_pk_mul_f32 v[188:189], v[12:13], v[188:189] op_sel:[1,0]
	v_cmp_gt_i32_e64 s[6:7], s15, v76
	v_pk_mul_f32 v[190:191], v[12:13], v[190:191] op_sel:[1,0]
	v_pk_fma_f32 v[188:189], v[188:189], v[54:55], v[58:59]
	v_sub_f32_e32 v183, v183, v12
	v_sub_f32_e32 v182, v182, v12
	v_cndmask_b32_e64 v161, v75, v71, s[6:7]
	v_cndmask_b32_e64 v160, v74, v70, s[6:7]
	v_pk_fma_f32 v[190:191], v[190:191], v[52:53], v[56:57]
	v_sub_f32_e32 v189, v189, v14
	v_sub_f32_e32 v188, v188, v14
	v_mov_b32_e32 v166, v15
	v_sub_f32_e32 v193, v199, v12
	v_sub_f32_e32 v192, v195, v12
	v_pk_mul_f32 v[182:183], v[12:13], v[182:183] op_sel:[1,0]
	s_movk_i32 s0, 0xf9f
	v_cndmask_b32_e64 v79, v67, v63, s[6:7]
	v_cndmask_b32_e64 v78, v66, v62, s[6:7]
	v_cndmask_b32_e64 v177, v73, v69, s[6:7]
	v_cndmask_b32_e64 v176, v72, v68, s[6:7]
	v_sub_f32_e32 v191, v191, v14
	v_sub_f32_e32 v190, v190, v14
	v_pk_mul_f32 v[188:189], v[166:167], v[188:189] op_sel_hi:[0,1]
	v_pk_add_f32 v[160:161], v[160:161], 1.0 op_sel_hi:[1,0]
	v_pk_mul_f32 v[192:193], v[12:13], v[192:193] op_sel:[1,0]
	v_pk_fma_f32 v[182:183], v[182:183], v[30:31], v[34:35]
	v_cmp_lt_i32_e64 s[0:1], s0, v140
	v_cndmask_b32_e64 v77, v65, v61, s[6:7]
	v_cndmask_b32_e64 v76, v64, v60, s[6:7]
	v_pk_mul_f32 v[190:191], v[166:167], v[190:191] op_sel_hi:[0,1]
	v_pk_add_f32 v[176:177], v[176:177], 1.0 op_sel_hi:[1,0]
	v_pk_fma_f32 v[78:79], v[188:189], v[160:161], v[78:79]
	v_cndmask_b32_e64 v189, v51, v43, s[6:7]
	v_cndmask_b32_e64 v188, v50, v42, s[6:7]
	v_pk_fma_f32 v[192:193], v[192:193], v[28:29], v[32:33]
	v_sub_f32_e32 v183, v183, v14
	v_sub_f32_e32 v182, v182, v14
	v_cndmask_b32_e64 v157, v1, v126, s[0:1]
	v_pk_fma_f32 v[76:77], v[190:191], v[176:177], v[76:77]
	v_cndmask_b32_e64 v177, v47, v39, s[6:7]
	v_cndmask_b32_e64 v176, v46, v38, s[6:7]
	v_cndmask_b32_e64 v191, v49, v41, s[6:7]
	v_cndmask_b32_e64 v190, v48, v40, s[6:7]
	v_sub_f32_e32 v193, v193, v14
	v_sub_f32_e32 v192, v192, v14
	v_pk_mul_f32 v[182:183], v[166:167], v[182:183] op_sel_hi:[0,1]
	v_pk_add_f32 v[188:189], v[188:189], 1.0 op_sel_hi:[1,0]
	v_lshlrev_b32_e32 v157, 1, v157
	s_waitcnt lgkmcnt(0)
	v_cndmask_b32_e64 v161, v45, v37, s[6:7]
	v_cndmask_b32_e64 v160, v44, v36, s[6:7]
	v_pk_mul_f32 v[192:193], v[166:167], v[192:193] op_sel_hi:[0,1]
	v_pk_add_f32 v[190:191], v[190:191], 1.0 op_sel_hi:[1,0]
	v_pk_fma_f32 v[176:177], v[182:183], v[188:189], v[176:177]
	v_add_u32_e32 v157, v127, v157
	v_cvt_pk_bf16_f32 v76, v76, v77
	v_sub_f32_e32 v183, v204, v8
	v_sub_f32_e32 v182, v206, v8
	v_sub_f32_e32 v189, v208, v8
	v_sub_f32_e32 v188, v202, v8
	v_pk_fma_f32 v[160:161], v[192:193], v[190:191], v[160:161]
	v_cvt_pk_bf16_f32 v77, v78, v79
	v_pk_mul_f32 v[188:189], v[8:9], v[188:189] op_sel:[1,0]
	v_cvt_pk_bf16_f32 v78, v160, v161
	v_cvt_pk_bf16_f32 v79, v176, v177
	ds_write_b16 v157, v76
	ds_write_b16_d16_hi v157, v76 offset:104
	ds_write_b16 v157, v77 offset:208
	ds_write_b16_d16_hi v157, v77 offset:312
	ds_write_b16 v157, v78 offset:416
	ds_write_b16_d16_hi v157, v78 offset:520
	ds_write_b16 v157, v79 offset:624
	ds_write_b16_d16_hi v157, v79 offset:728
	v_add_u32_e32 v76, 0x70, v140
	v_pk_mul_f32 v[182:183], v[8:9], v[182:183] op_sel:[1,0]
	v_cmp_gt_i32_e64 s[8:9], s15, v76
	v_pk_fma_f32 v[182:183], v[182:183], v[52:53], v[56:57]
	v_pk_fma_f32 v[188:189], v[188:189], v[54:55], v[58:59]
	v_sub_f32_e32 v191, v209, v8
	v_sub_f32_e32 v190, v207, v8
	v_sub_f32_e32 v193, v201, v8
	v_sub_f32_e32 v192, v200, v8
	v_cndmask_b32_e64 v161, v75, v71, s[8:9]
	v_cndmask_b32_e64 v160, v74, v70, s[8:9]
	v_cndmask_b32_e64 v177, v73, v69, s[8:9]
	v_cndmask_b32_e64 v176, v72, v68, s[8:9]
	v_sub_f32_e32 v189, v189, v10
	v_sub_f32_e32 v188, v188, v10
	v_sub_f32_e32 v183, v183, v10
	v_sub_f32_e32 v182, v182, v10
	v_mov_b32_e32 v166, v11
	v_pk_mul_f32 v[192:193], v[8:9], v[192:193] op_sel:[1,0]
	v_pk_mul_f32 v[190:191], v[8:9], v[190:191] op_sel:[1,0]
	v_cndmask_b32_e64 v77, v65, v61, s[8:9]
	v_cndmask_b32_e64 v76, v64, v60, s[8:9]
	v_cndmask_b32_e64 v79, v67, v63, s[8:9]
	v_cndmask_b32_e64 v78, v66, v62, s[8:9]
	v_pk_mul_f32 v[182:183], v[166:167], v[182:183] op_sel_hi:[0,1]
	v_pk_mul_f32 v[188:189], v[166:167], v[188:189] op_sel_hi:[0,1]
	v_pk_add_f32 v[176:177], v[176:177], 1.0 op_sel_hi:[1,0]
	v_pk_add_f32 v[160:161], v[160:161], 1.0 op_sel_hi:[1,0]
	v_pk_fma_f32 v[190:191], v[190:191], v[28:29], v[32:33]
	v_pk_fma_f32 v[192:193], v[192:193], v[30:31], v[34:35]
	v_pk_fma_f32 v[78:79], v[188:189], v[160:161], v[78:79]
	v_pk_fma_f32 v[76:77], v[182:183], v[176:177], v[76:77]
	v_cndmask_b32_e64 v183, v51, v43, s[8:9]
	v_cndmask_b32_e64 v182, v50, v42, s[8:9]
	v_cndmask_b32_e64 v189, v49, v41, s[8:9]
	v_cndmask_b32_e64 v188, v48, v40, s[8:9]
	v_sub_f32_e32 v193, v193, v10
	v_sub_f32_e32 v192, v192, v10
	v_sub_f32_e32 v191, v191, v10
	v_sub_f32_e32 v190, v190, v10
	s_movk_i32 s0, 0xf8f
	v_cndmask_b32_e64 v161, v45, v37, s[8:9]
	v_cndmask_b32_e64 v160, v44, v36, s[8:9]
	v_cndmask_b32_e64 v177, v47, v39, s[8:9]
	v_cndmask_b32_e64 v176, v46, v38, s[8:9]
	v_pk_mul_f32 v[190:191], v[166:167], v[190:191] op_sel_hi:[0,1]
	v_pk_mul_f32 v[192:193], v[166:167], v[192:193] op_sel_hi:[0,1]
	v_pk_add_f32 v[188:189], v[188:189], 1.0 op_sel_hi:[1,0]
	v_pk_add_f32 v[182:183], v[182:183], 1.0 op_sel_hi:[1,0]
	v_cmp_lt_i32_e64 s[0:1], s0, v140
	v_pk_fma_f32 v[176:177], v[192:193], v[182:183], v[176:177]
	v_pk_fma_f32 v[182:183], v[190:191], v[188:189], v[160:161]
	v_cndmask_b32_e64 v160, v1, v126, s[0:1]
	v_lshlrev_b32_e32 v160, 1, v160
	v_add_u32_e32 v160, v127, v160
	v_cvt_pk_bf16_f32 v76, v76, v77
	v_cvt_pk_bf16_f32 v77, v78, v79
	v_cvt_pk_bf16_f32 v78, v182, v183
	v_cvt_pk_bf16_f32 v79, v176, v177
	ds_write_b16 v160, v76 offset:32
	ds_write_b16_d16_hi v160, v76 offset:136
	ds_write_b16 v160, v77 offset:240
	ds_write_b16_d16_hi v160, v77 offset:344
	ds_write_b16 v160, v78 offset:448
	ds_write_b16_d16_hi v160, v78 offset:552
	ds_write_b16 v160, v79 offset:656
	ds_write_b16_d16_hi v160, v79 offset:760
	v_add_u32_e32 v76, 0x80, v140
	v_cmp_gt_i32_e64 s[10:11], s15, v76
	s_movk_i32 s0, 0xf7f
	v_cmp_lt_i32_e64 s[0:1], s0, v140
	v_cndmask_b32_e64 v63, v67, v63, s[10:11]
	v_cndmask_b32_e64 v62, v66, v62, s[10:11]
	v_cndmask_b32_e64 v67, v73, v69, s[10:11]
	v_cndmask_b32_e64 v66, v72, v68, s[10:11]
	v_sub_f32_e32 v69, v214, v4
	v_sub_f32_e32 v68, v216, v4
	v_cndmask_b32_e64 v37, v45, v37, s[10:11]
	v_cndmask_b32_e64 v36, v44, v36, s[10:11]
	v_sub_f32_e32 v45, v219, v4
	v_sub_f32_e32 v44, v217, v4
	v_cndmask_b32_e64 v61, v65, v61, s[10:11]
	v_cndmask_b32_e64 v60, v64, v60, s[10:11]
	v_cndmask_b32_e64 v65, v75, v71, s[10:11]
	v_cndmask_b32_e64 v64, v74, v70, s[10:11]
	v_sub_f32_e32 v71, v218, v4
	v_sub_f32_e32 v70, v212, v4
	v_pk_mul_f32 v[68:69], v[4:5], v[68:69] op_sel:[1,0]
	v_cndmask_b32_e64 v39, v47, v39, s[10:11]
	v_cndmask_b32_e64 v38, v46, v38, s[10:11]
	v_sub_f32_e32 v47, v211, v4
	v_sub_f32_e32 v46, v210, v4
	v_pk_mul_f32 v[44:45], v[4:5], v[44:45] op_sel:[1,0]
	v_pk_mul_f32 v[70:71], v[4:5], v[70:71] op_sel:[1,0]
	v_pk_fma_f32 v[52:53], v[68:69], v[52:53], v[56:57]
	v_pk_mul_f32 v[46:47], v[4:5], v[46:47] op_sel:[1,0]
	v_pk_fma_f32 v[28:29], v[44:45], v[28:29], v[32:33]
	v_pk_fma_f32 v[54:55], v[70:71], v[54:55], v[58:59]
	v_sub_f32_e32 v53, v53, v6
	v_sub_f32_e32 v52, v52, v6
	v_mov_b32_e32 v56, v7
	v_cndmask_b32_e64 v41, v49, v41, s[10:11]
	v_cndmask_b32_e64 v40, v48, v40, s[10:11]
	v_pk_fma_f32 v[30:31], v[46:47], v[30:31], v[34:35]
	v_sub_f32_e32 v29, v29, v6
	v_sub_f32_e32 v28, v28, v6
	v_cndmask_b32_e64 v1, v1, v126, s[0:1]
	v_sub_f32_e32 v55, v55, v6
	v_sub_f32_e32 v54, v54, v6
	v_pk_mul_f32 v[52:53], v[56:57], v[52:53] op_sel_hi:[0,1]
	v_pk_add_f32 v[58:59], v[66:67], 1.0 op_sel_hi:[1,0]
	v_cndmask_b32_e64 v43, v51, v43, s[10:11]
	v_cndmask_b32_e64 v42, v50, v42, s[10:11]
	v_sub_f32_e32 v31, v31, v6
	v_sub_f32_e32 v30, v30, v6
	v_pk_mul_f32 v[28:29], v[56:57], v[28:29] op_sel_hi:[0,1]
	v_pk_add_f32 v[32:33], v[40:41], 1.0 op_sel_hi:[1,0]
	v_lshlrev_b32_e32 v1, 1, v1
	v_pk_mul_f32 v[54:55], v[56:57], v[54:55] op_sel_hi:[0,1]
	v_pk_add_f32 v[64:65], v[64:65], 1.0 op_sel_hi:[1,0]
	v_pk_fma_f32 v[52:53], v[52:53], v[58:59], v[60:61]
	v_pk_mul_f32 v[30:31], v[56:57], v[30:31] op_sel_hi:[0,1]
	v_pk_add_f32 v[34:35], v[42:43], 1.0 op_sel_hi:[1,0]
	v_pk_fma_f32 v[28:29], v[28:29], v[32:33], v[36:37]
	v_add_u32_e32 v161, v127, v1
	v_cvt_pk_bf16_f32 v1, v52, v53
	v_pk_fma_f32 v[54:55], v[54:55], v[64:65], v[62:63]
	v_pk_fma_f32 v[30:31], v[30:31], v[34:35], v[38:39]
	v_cvt_pk_bf16_f32 v32, v54, v55
	v_cvt_pk_bf16_f32 v28, v28, v29
	s_addk_i32 s12, 0x60
	v_cvt_pk_bf16_f32 v29, v30, v31
	ds_write_b16 v161, v1 offset:64
	ds_write_b16_d16_hi v161, v1 offset:168
	ds_write_b16 v161, v32 offset:272
	ds_write_b16_d16_hi v161, v32 offset:376
	ds_write_b16 v161, v28 offset:480
	ds_write_b16_d16_hi v161, v28 offset:584
	ds_write_b16 v161, v29 offset:688
	ds_write_b16_d16_hi v161, v29 offset:792
	s_waitcnt lgkmcnt(0)
	ds_read2_b64 v[28:31], v117 offset1:1
	v_add_u32_e32 v32, s12, v158
	v_lshlrev_b32_e32 v1, 2, v32
	v_cmp_gt_i32_e64 s[22:23], s38, v32
	v_and_b32_e32 v176, 0xf0, v32
	v_and_b32_e32 v177, 0xfffc00, v1
	s_and_saveexec_b64 s[0:1], s[22:23]
	s_xor_b64 s[0:1], exec, s[0:1]
	v_add_lshl_u32 v1, v177, v150, 8
	v_or3_b32 v1, v1, v176, v2
	s_or_saveexec_b64 s[0:1], s[0:1]
	v_add_u32_e32 v33, 0x3ff000, v32
	v_lshrrev_b32_e32 v32, 1, v32
	v_lshrrev_b32_e32 v182, 2, v33
	v_and_or_b32 v183, v32, s27, v141
	s_xor_b64 exec, exec, s[0:1]
	v_and_b32_e32 v1, 0xffc00, v182
	v_add_u32_e32 v1, v1, v150
	v_lshl_or_b32 v1, v1, 12, v183
	v_add_u32_e32 v1, 0x400000, v1
	s_or_b64 exec, exec, s[0:1]
	v_lshlrev_b32_e32 v1, 1, v1
	s_waitcnt lgkmcnt(0)
	global_store_dwordx4 v1, v[28:31], s[60:61]
	ds_read2_b64 v[28:31], v152 offset1:1
	v_add_u32_e32 v32, s12, v159
	v_lshlrev_b32_e32 v1, 2, v32
	v_cmp_gt_i32_e64 s[14:15], s38, v32
	v_and_b32_e32 v163, 0xf0, v32
	v_and_b32_e32 v165, 0xfffc00, v1
	s_and_saveexec_b64 s[0:1], s[14:15]
	s_xor_b64 s[0:1], exec, s[0:1]
	v_add_lshl_u32 v1, v165, v151, 8
	v_or3_b32 v1, v1, v163, v2
	s_or_saveexec_b64 s[0:1], s[0:1]
	v_add_u32_e32 v33, 0x3ff000, v32
	v_lshrrev_b32_e32 v32, 1, v32
	v_lshrrev_b32_e32 v175, 2, v33
	v_and_or_b32 v179, v32, s27, v141
	s_xor_b64 exec, exec, s[0:1]
	v_and_b32_e32 v1, 0xffc00, v175
	v_add_u32_e32 v1, v1, v151
	v_lshl_or_b32 v1, v1, 12, v179
	v_add_u32_e32 v1, 0x400000, v1
	s_or_b64 exec, exec, s[0:1]
	v_lshlrev_b32_e32 v1, 1, v1
	s_waitcnt lgkmcnt(0)
	global_store_dwordx4 v1, v[28:31], s[60:61]
	ds_read2_b64 v[28:31], v153 offset1:1
	v_add_u32_e32 v1, s12, v162
	v_lshlrev_b32_e32 v32, 2, v1
	v_cmp_gt_i32_e64 s[12:13], s38, v1
	v_and_b32_e32 v158, 0xf0, v1
	v_and_b32_e32 v159, 0xfffc00, v32
	s_and_saveexec_b64 s[0:1], s[12:13]
	s_xor_b64 s[0:1], exec, s[0:1]
	v_add_lshl_u32 v0, v159, v0, 8
	v_or3_b32 v32, v0, v158, v2
	s_or_saveexec_b64 s[0:1], s[0:1]
	v_add_u32_e32 v33, 0x3ff000, v1
	v_lshrrev_b32_e32 v1, 1, v1
	v_lshrrev_b32_e32 v162, 2, v33
	v_and_or_b32 v166, v1, s27, v141
	s_xor_b64 exec, exec, s[0:1]
	v_and_b32_e32 v1, 0xffc00, v162
	v_add_u32_e32 v0, v1, v0
	v_lshl_or_b32 v0, v0, 12, v166
	v_add_u32_e32 v32, 0x400000, v0
	s_or_b64 exec, exec, s[0:1]
	v_lshlrev_b32_e32 v32, 1, v32
	s_waitcnt lgkmcnt(0)
	global_store_dwordx4 v32, v[28:31], s[60:61]
	s_waitcnt lgkmcnt(0)
	v_readlane_b32 s40, v255, 19
	v_readlane_b32 s46, v255, 25
	v_add_u32_e32 v28, 0x80, v187
	v_readlane_b32 s47, v255, 26
	v_ashrrev_i32_e32 v29, 31, v28
	v_lshlrev_b64 v[28:29], 2, v[28:29]
	v_readlane_b32 s48, v255, 27
	v_readlane_b32 s49, v255, 28
	v_lshl_add_u64 v[40:41], s[80:81], 0, v[28:29]
	v_lshl_add_u64 v[32:33], s[46:47], 0, v[28:29]
	v_lshl_add_u64 v[36:37], s[48:49], 0, v[28:29]
	v_lshl_add_u64 v[64:65], s[82:83], 0, v[28:29]
	v_lshl_add_u64 v[42:43], v[40:41], 0, s[72:73]
	global_load_dwordx4 v[28:31], v[32:33], off offset:16
	global_load_dwordx4 v[44:47], v[32:33], off
	s_nop 0
	global_load_dwordx4 v[32:35], v[36:37], off offset:16
	global_load_dwordx4 v[48:51], v[36:37], off
	s_nop 0
	global_load_dwordx4 v[36:39], v[40:41], off offset:16
	global_load_dwordx4 v[60:63], v[40:41], off
	v_add_co_u32_e64 v40, s[0:1], s38, v40
	v_lshl_add_u64 v[66:67], v[64:65], 0, s[72:73]
	s_nop 0
	v_addc_co_u32_e64 v41, s[0:1], 0, v41, s[0:1]
	global_load_dwordx4 v[56:59], v[40:41], off
	s_nop 0
	global_load_dwordx4 v[40:43], v[42:43], off offset:16
	s_nop 0
	global_load_dwordx4 v[52:55], v[64:65], off offset:16
	global_load_dwordx4 v[68:71], v[64:65], off
	v_add_co_u32_e64 v64, s[0:1], s38, v64
	v_mov_b32_e32 v150, v25
	s_nop 0
	v_addc_co_u32_e64 v65, s[0:1], 0, v65, s[0:1]
	global_load_dwordx4 v[72:75], v[64:65], off
	s_nop 0
	global_load_dwordx4 v[64:67], v[66:67], off offset:16
	v_mov_b32_e32 v151, v25
	v_sub_f32_e32 v87, v87, v24
	v_sub_f32_e32 v86, v86, v24
	v_sub_f32_e32 v85, v85, v24
	v_sub_f32_e32 v84, v84, v24
	v_mov_b32_e32 v196, v25
	v_mov_b32_e32 v197, v25
	v_pk_mul_f32 v[86:87], v[150:151], v[86:87]
	v_pk_mul_f32 v[84:85], v[196:197], v[84:85]
	v_sub_f32_e32 v81, v81, v24
	v_sub_f32_e32 v80, v80, v24
	v_sub_f32_e32 v25, v83, v24
	v_sub_f32_e32 v24, v82, v24
	v_mov_b32_e32 v140, v27
	v_mov_b32_e32 v141, v27
	v_pk_mul_f32 v[24:25], v[196:197], v[24:25]
	v_pk_mul_f32 v[80:81], v[150:151], v[80:81]
	v_mov_b32_e32 v198, v27
	v_mov_b32_e32 v199, v27
	v_mov_b32_e32 v126, v21
	v_mov_b32_e32 v127, v21
	v_sub_f32_e32 v89, v89, v20
	v_sub_f32_e32 v88, v88, v20
	v_mov_b32_e32 v78, v23
	v_mov_b32_e32 v79, v23
	v_pk_mul_f32 v[88:89], v[126:127], v[88:89]
	v_mov_b32_e32 v76, v17
	v_mov_b32_e32 v77, v17
	v_mov_b32_e32 v0, v19
	v_mov_b32_e32 v1, v19
	s_addk_i32 s75, 0x80
	v_readlane_b32 s41, v255, 20
	v_readlane_b32 s42, v255, 21
	v_readlane_b32 s43, v255, 22
	v_readlane_b32 s44, v255, 23
	v_readlane_b32 s45, v255, 24
	v_readlane_b32 s50, v255, 29
	v_readlane_b32 s51, v255, 30
	v_readlane_b32 s52, v255, 31
	v_readlane_b32 s53, v255, 32
	v_readlane_b32 s54, v255, 33
	v_readlane_b32 s55, v255, 34
	s_waitcnt vmcnt(9)
	v_pk_fma_f32 v[80:81], v[80:81], v[28:29], v[32:33]
	s_waitcnt vmcnt(8)
	v_pk_fma_f32 v[86:87], v[86:87], v[44:45], v[48:49]
	v_pk_fma_f32 v[84:85], v[84:85], v[46:47], v[50:51]
	v_sub_f32_e32 v87, v87, v26
	v_sub_f32_e32 v86, v86, v26
	v_sub_f32_e32 v85, v85, v26
	v_sub_f32_e32 v84, v84, v26
	v_pk_mul_f32 v[86:87], v[140:141], v[86:87]
	v_pk_fma_f32 v[24:25], v[24:25], v[30:31], v[34:35]
	s_waitcnt vmcnt(2)
	v_cndmask_b32_e64 v189, v69, v61, s[24:25]
	v_cndmask_b32_e64 v188, v68, v60, s[24:25]
	v_cndmask_b32_e64 v191, v71, v63, s[24:25]
	v_cndmask_b32_e64 v190, v70, v62, s[24:25]
	v_pk_mul_f32 v[84:85], v[198:199], v[84:85]
	s_waitcnt vmcnt(1)
	v_cndmask_b32_e64 v195, v73, v57, s[24:25]
	v_cndmask_b32_e64 v194, v72, v56, s[24:25]
	v_cndmask_b32_e64 v193, v75, v59, s[24:25]
	v_cndmask_b32_e64 v192, v74, v58, s[24:25]
	v_pk_add_f32 v[194:195], v[194:195], 1.0 op_sel_hi:[1,0]
	v_pk_add_f32 v[192:193], v[192:193], 1.0 op_sel_hi:[1,0]
	v_pk_fma_f32 v[86:87], v[86:87], v[194:195], v[188:189]
	s_waitcnt vmcnt(0)
	v_cndmask_b32_e64 v195, v65, v41, s[24:25]
	v_cndmask_b32_e64 v194, v64, v40, s[24:25]
	v_sub_f32_e32 v25, v25, v26
	v_sub_f32_e32 v24, v24, v26
	v_sub_f32_e32 v27, v81, v26
	v_sub_f32_e32 v26, v80, v26
	v_pk_fma_f32 v[84:85], v[84:85], v[192:193], v[190:191]
	v_cndmask_b32_e64 v189, v53, v37, s[24:25]
	v_cndmask_b32_e64 v188, v52, v36, s[24:25]
	v_pk_mul_f32 v[26:27], v[140:141], v[26:27]
	v_pk_add_f32 v[80:81], v[194:195], 1.0 op_sel_hi:[1,0]
	v_cndmask_b32_e64 v193, v67, v43, s[24:25]
	v_cndmask_b32_e64 v192, v66, v42, s[24:25]
	v_pk_fma_f32 v[26:27], v[26:27], v[80:81], v[188:189]
	v_cvt_pk_bf16_f32 v80, v86, v87
	v_cvt_pk_bf16_f32 v81, v84, v85
	v_sub_f32_e32 v85, v93, v20
	v_sub_f32_e32 v84, v92, v20
	v_sub_f32_e32 v87, v95, v20
	v_sub_f32_e32 v86, v94, v20
	v_mov_b32_e32 v92, v21
	v_mov_b32_e32 v93, v21
	v_cndmask_b32_e64 v191, v55, v39, s[24:25]
	v_cndmask_b32_e64 v190, v54, v38, s[24:25]
	v_pk_mul_f32 v[24:25], v[198:199], v[24:25]
	v_pk_add_f32 v[82:83], v[192:193], 1.0 op_sel_hi:[1,0]
	v_pk_mul_f32 v[86:87], v[92:93], v[86:87]
	v_pk_mul_f32 v[84:85], v[126:127], v[84:85]
	v_pk_fma_f32 v[24:25], v[24:25], v[82:83], v[190:191]
	v_pk_fma_f32 v[84:85], v[84:85], v[44:45], v[48:49]
	v_pk_fma_f32 v[86:87], v[86:87], v[46:47], v[50:51]
	v_sub_f32_e32 v21, v91, v20
	v_sub_f32_e32 v20, v90, v20
	v_cvt_pk_bf16_f32 v26, v26, v27
	v_cvt_pk_bf16_f32 v24, v24, v25
	ds_write_b16 v154, v80
	ds_write_b16_d16_hi v154, v80 offset:104
	ds_write_b16 v154, v81 offset:208
	ds_write_b16_d16_hi v154, v81 offset:312
	ds_write_b16 v154, v26 offset:416
	ds_write_b16_d16_hi v154, v26 offset:520
	ds_write_b16 v154, v24 offset:624
	ds_write_b16_d16_hi v154, v24 offset:728
	v_cndmask_b32_e32 v81, v75, v59, vcc
	v_cndmask_b32_e32 v80, v74, v58, vcc
	v_cndmask_b32_e32 v83, v73, v57, vcc
	v_cndmask_b32_e32 v82, v72, v56, vcc
	v_sub_f32_e32 v87, v87, v22
	v_sub_f32_e32 v86, v86, v22
	v_sub_f32_e32 v85, v85, v22
	v_sub_f32_e32 v84, v84, v22
	v_mov_b32_e32 v94, v23
	v_mov_b32_e32 v95, v23
	v_pk_mul_f32 v[20:21], v[92:93], v[20:21]
	v_cndmask_b32_e32 v25, v69, v61, vcc
	v_cndmask_b32_e32 v24, v68, v60, vcc
	v_cndmask_b32_e32 v27, v71, v63, vcc
	v_cndmask_b32_e32 v26, v70, v62, vcc
	v_pk_mul_f32 v[84:85], v[78:79], v[84:85]
	v_pk_mul_f32 v[86:87], v[94:95], v[86:87]
	v_pk_add_f32 v[82:83], v[82:83], 1.0 op_sel_hi:[1,0]
	v_pk_add_f32 v[80:81], v[80:81], 1.0 op_sel_hi:[1,0]
	v_pk_fma_f32 v[88:89], v[88:89], v[28:29], v[32:33]
	v_pk_fma_f32 v[20:21], v[20:21], v[30:31], v[34:35]
	v_pk_fma_f32 v[26:27], v[86:87], v[80:81], v[26:27]
	v_pk_fma_f32 v[24:25], v[84:85], v[82:83], v[24:25]
	v_cndmask_b32_e32 v85, v67, v43, vcc
	v_cndmask_b32_e32 v84, v66, v42, vcc
	v_cndmask_b32_e32 v87, v65, v41, vcc
	v_cndmask_b32_e32 v86, v64, v40, vcc
	v_sub_f32_e32 v21, v21, v22
	v_sub_f32_e32 v20, v20, v22
	v_sub_f32_e32 v23, v89, v22
	v_sub_f32_e32 v22, v88, v22
	v_cndmask_b32_e32 v81, v53, v37, vcc
	v_cndmask_b32_e32 v80, v52, v36, vcc
	v_cndmask_b32_e32 v83, v55, v39, vcc
	v_cndmask_b32_e32 v82, v54, v38, vcc
	v_pk_mul_f32 v[22:23], v[78:79], v[22:23]
	v_pk_mul_f32 v[20:21], v[94:95], v[20:21]
	v_pk_add_f32 v[78:79], v[86:87], 1.0 op_sel_hi:[1,0]
	v_pk_add_f32 v[84:85], v[84:85], 1.0 op_sel_hi:[1,0]
	v_pk_fma_f32 v[22:23], v[22:23], v[78:79], v[80:81]
	v_pk_fma_f32 v[20:21], v[20:21], v[84:85], v[82:83]
	v_sub_f32_e32 v81, v107, v16
	v_sub_f32_e32 v80, v106, v16
	v_mov_b32_e32 v82, v17
	v_mov_b32_e32 v83, v17
	v_sub_f32_e32 v79, v105, v16
	v_sub_f32_e32 v78, v104, v16
	v_pk_mul_f32 v[80:81], v[82:83], v[80:81]
	v_cvt_pk_bf16_f32 v24, v24, v25
	v_cvt_pk_bf16_f32 v25, v26, v27
	v_pk_mul_f32 v[78:79], v[76:77], v[78:79]
	v_pk_fma_f32 v[80:81], v[80:81], v[46:47], v[50:51]
	v_sub_f32_e32 v87, v97, v16
	v_sub_f32_e32 v86, v96, v16
	v_sub_f32_e32 v17, v99, v16
	v_sub_f32_e32 v16, v98, v16
	v_cvt_pk_bf16_f32 v22, v22, v23
	v_cvt_pk_bf16_f32 v20, v20, v21
	ds_write_b16 v155, v24 offset:32
	ds_write_b16_d16_hi v155, v24 offset:136
	ds_write_b16 v155, v25 offset:240
	ds_write_b16_d16_hi v155, v25 offset:344
	ds_write_b16 v155, v22 offset:448
	ds_write_b16_d16_hi v155, v22 offset:552
	ds_write_b16 v155, v20 offset:656
	ds_write_b16_d16_hi v155, v20 offset:760
	v_cndmask_b32_e64 v25, v75, v59, s[4:5]
	v_cndmask_b32_e64 v24, v74, v58, s[4:5]
	v_pk_fma_f32 v[78:79], v[78:79], v[44:45], v[48:49]
	v_sub_f32_e32 v81, v81, v18
	v_sub_f32_e32 v80, v80, v18
	v_mov_b32_e32 v84, v19
	v_mov_b32_e32 v85, v19
	v_pk_mul_f32 v[16:17], v[82:83], v[16:17]
	v_pk_mul_f32 v[76:77], v[76:77], v[86:87]
	v_cndmask_b32_e64 v23, v71, v63, s[4:5]
	v_cndmask_b32_e64 v22, v70, v62, s[4:5]
	v_cndmask_b32_e64 v27, v73, v57, s[4:5]
	v_cndmask_b32_e64 v26, v72, v56, s[4:5]
	v_sub_f32_e32 v79, v79, v18
	v_sub_f32_e32 v78, v78, v18
	v_pk_mul_f32 v[80:81], v[84:85], v[80:81]
	v_pk_add_f32 v[24:25], v[24:25], 1.0 op_sel_hi:[1,0]
	v_pk_fma_f32 v[76:77], v[76:77], v[28:29], v[32:33]
	v_pk_fma_f32 v[16:17], v[16:17], v[30:31], v[34:35]
	v_cndmask_b32_e64 v21, v69, v61, s[4:5]
	v_cndmask_b32_e64 v20, v68, v60, s[4:5]
	v_pk_mul_f32 v[78:79], v[0:1], v[78:79]
	v_pk_add_f32 v[26:27], v[26:27], 1.0 op_sel_hi:[1,0]
	v_pk_fma_f32 v[22:23], v[80:81], v[24:25], v[22:23]
	v_cndmask_b32_e64 v81, v65, v41, s[4:5]
	v_cndmask_b32_e64 v80, v64, v40, s[4:5]
	v_sub_f32_e32 v17, v17, v18
	v_sub_f32_e32 v16, v16, v18
	v_sub_f32_e32 v19, v77, v18
	v_sub_f32_e32 v18, v76, v18
	v_pk_fma_f32 v[20:21], v[78:79], v[26:27], v[20:21]
	v_cndmask_b32_e64 v25, v53, v37, s[4:5]
	v_cndmask_b32_e64 v24, v52, v36, s[4:5]
	v_cndmask_b32_e64 v79, v67, v43, s[4:5]
	v_cndmask_b32_e64 v78, v66, v42, s[4:5]
	v_pk_mul_f32 v[0:1], v[0:1], v[18:19]
	v_pk_add_f32 v[18:19], v[80:81], 1.0 op_sel_hi:[1,0]
	v_cndmask_b32_e64 v27, v55, v39, s[4:5]
	v_cndmask_b32_e64 v26, v54, v38, s[4:5]
	v_pk_mul_f32 v[16:17], v[84:85], v[16:17]
	v_pk_add_f32 v[76:77], v[78:79], 1.0 op_sel_hi:[1,0]
	v_pk_fma_f32 v[0:1], v[0:1], v[18:19], v[24:25]
	v_cvt_pk_bf16_f32 v18, v20, v21
	v_pk_fma_f32 v[16:17], v[16:17], v[76:77], v[26:27]
	v_cvt_pk_bf16_f32 v19, v22, v23
	v_cvt_pk_bf16_f32 v0, v0, v1
	v_add_u32_e32 v22, s75, v164
	v_cvt_pk_bf16_f32 v1, v16, v17
	ds_write_b16 v156, v18 offset:64
	ds_write_b16_d16_hi v156, v18 offset:168
	ds_write_b16 v156, v19 offset:272
	ds_write_b16_d16_hi v156, v19 offset:376
	ds_write_b16 v156, v0 offset:480
	ds_write_b16_d16_hi v156, v0 offset:584
	ds_write_b16 v156, v1 offset:688
	ds_write_b16_d16_hi v156, v1 offset:792
	s_waitcnt lgkmcnt(0)
	ds_read2_b64 v[16:19], v117 offset1:1
	s_and_saveexec_b64 s[0:1], s[16:17]
	s_xor_b64 s[0:1], exec, s[0:1]
	v_add_lshl_u32 v0, v170, v22, 8
	v_or3_b32 v0, v0, v167, v2
	s_andn2_saveexec_b64 s[0:1], s[0:1]
	v_and_b32_e32 v0, 0xffc00, v178
	v_add_u32_e32 v0, v0, v22
	v_lshl_or_b32 v0, v0, 12, v184
	v_add_u32_e32 v0, 0x400000, v0
	s_or_b64 exec, exec, s[0:1]
	v_lshlrev_b32_e32 v0, 1, v0
	s_waitcnt lgkmcnt(0)
	global_store_dwordx4 v0, v[16:19], s[60:61]
	ds_read2_b64 v[16:19], v152 offset1:1
	v_add_u32_e32 v23, s75, v168
	s_and_saveexec_b64 s[0:1], s[18:19]
	s_xor_b64 s[0:1], exec, s[0:1]
	v_add_lshl_u32 v0, v174, v23, 8
	v_or3_b32 v0, v0, v172, v2
	s_andn2_saveexec_b64 s[0:1], s[0:1]
	v_and_b32_e32 v0, 0xffc00, v180
	v_add_u32_e32 v0, v0, v23
	v_lshl_or_b32 v0, v0, 12, v185
	v_add_u32_e32 v0, 0x400000, v0
	s_or_b64 exec, exec, s[0:1]
	v_lshlrev_b32_e32 v0, 1, v0
	s_waitcnt lgkmcnt(0)
	global_store_dwordx4 v0, v[16:19], s[60:61]
	ds_read2_b64 v[16:19], v153 offset1:1
	v_add_u32_e32 v24, s75, v169
	s_and_saveexec_b64 s[0:1], s[20:21]
	s_xor_b64 s[0:1], exec, s[0:1]
	v_add_lshl_u32 v0, v173, v24, 8
	v_or3_b32 v25, v0, v171, v2
	s_andn2_saveexec_b64 s[0:1], s[0:1]
	v_and_b32_e32 v0, 0xffc00, v181
	v_add_u32_e32 v0, v0, v24
	v_lshl_or_b32 v0, v0, 12, v186
	v_add_u32_e32 v25, 0x400000, v0
	s_or_b64 exec, exec, s[0:1]
	v_sub_f32_e32 v89, v131, v12
	v_sub_f32_e32 v88, v130, v12
	v_mov_b32_e32 v90, v13
	v_mov_b32_e32 v91, v13
	v_mov_b32_e32 v26, v13
	v_mov_b32_e32 v27, v13
	v_sub_f32_e32 v87, v129, v12
	v_sub_f32_e32 v86, v128, v12
	v_pk_mul_f32 v[88:89], v[90:91], v[88:89]
	v_pk_mul_f32 v[86:87], v[26:27], v[86:87]
	v_pk_fma_f32 v[88:89], v[88:89], v[46:47], v[50:51]
	v_sub_f32_e32 v95, v101, v12
	v_sub_f32_e32 v94, v100, v12
	v_sub_f32_e32 v13, v103, v12
	v_sub_f32_e32 v12, v102, v12
	v_lshlrev_b32_e32 v25, 1, v25
	v_cndmask_b32_e64 v83, v75, v59, s[6:7]
	v_cndmask_b32_e64 v82, v74, v58, s[6:7]
	v_pk_fma_f32 v[86:87], v[86:87], v[44:45], v[48:49]
	v_sub_f32_e32 v89, v89, v14
	v_sub_f32_e32 v88, v88, v14
	v_mov_b32_e32 v92, v15
	v_mov_b32_e32 v93, v15
	v_pk_mul_f32 v[12:13], v[90:91], v[12:13]
	v_pk_mul_f32 v[26:27], v[26:27], v[94:95]
	v_mov_b32_e32 v76, v15
	v_mov_b32_e32 v77, v15
	s_waitcnt lgkmcnt(0)
	global_store_dwordx4 v25, v[16:19], s[60:61]
	v_cndmask_b32_e64 v85, v73, v57, s[6:7]
	v_cndmask_b32_e64 v84, v72, v56, s[6:7]
	v_cndmask_b32_e64 v19, v71, v63, s[6:7]
	v_cndmask_b32_e64 v18, v70, v62, s[6:7]
	v_sub_f32_e32 v87, v87, v14
	v_sub_f32_e32 v86, v86, v14
	v_pk_mul_f32 v[88:89], v[92:93], v[88:89]
	v_pk_add_f32 v[82:83], v[82:83], 1.0 op_sel_hi:[1,0]
	v_pk_fma_f32 v[26:27], v[26:27], v[28:29], v[32:33]
	v_pk_fma_f32 v[12:13], v[12:13], v[30:31], v[34:35]
	v_cndmask_b32_e64 v17, v69, v61, s[6:7]
	v_cndmask_b32_e64 v16, v68, v60, s[6:7]
	v_pk_mul_f32 v[86:87], v[76:77], v[86:87]
	v_pk_add_f32 v[84:85], v[84:85], 1.0 op_sel_hi:[1,0]
	v_pk_fma_f32 v[18:19], v[88:89], v[82:83], v[18:19]
	v_cndmask_b32_e64 v89, v65, v41, s[6:7]
	v_cndmask_b32_e64 v88, v64, v40, s[6:7]
	v_sub_f32_e32 v13, v13, v14
	v_sub_f32_e32 v12, v12, v14
	v_sub_f32_e32 v15, v27, v14
	v_sub_f32_e32 v14, v26, v14
	v_pk_fma_f32 v[16:17], v[86:87], v[84:85], v[16:17]
	v_cndmask_b32_e64 v83, v53, v37, s[6:7]
	v_cndmask_b32_e64 v82, v52, v36, s[6:7]
	v_cndmask_b32_e64 v87, v67, v43, s[6:7]
	v_cndmask_b32_e64 v86, v66, v42, s[6:7]
	v_pk_mul_f32 v[14:15], v[76:77], v[14:15]
	v_pk_add_f32 v[26:27], v[88:89], 1.0 op_sel_hi:[1,0]
	v_mov_b32_e32 v78, v9
	v_mov_b32_e32 v79, v9
	v_cndmask_b32_e64 v85, v55, v39, s[6:7]
	v_cndmask_b32_e64 v84, v54, v38, s[6:7]
	v_pk_mul_f32 v[12:13], v[92:93], v[12:13]
	v_pk_add_f32 v[76:77], v[86:87], 1.0 op_sel_hi:[1,0]
	v_pk_fma_f32 v[14:15], v[14:15], v[26:27], v[82:83]
	v_sub_f32_e32 v27, v137, v8
	v_sub_f32_e32 v26, v136, v8
	v_pk_fma_f32 v[12:13], v[12:13], v[76:77], v[84:85]
	v_sub_f32_e32 v77, v139, v8
	v_sub_f32_e32 v76, v138, v8
	v_mov_b32_e32 v82, v9
	v_mov_b32_e32 v83, v9
	v_pk_mul_f32 v[26:27], v[78:79], v[26:27]
	v_pk_mul_f32 v[76:77], v[82:83], v[76:77]
	v_pk_fma_f32 v[26:27], v[26:27], v[44:45], v[48:49]
	v_sub_f32_e32 v87, v133, v8
	v_sub_f32_e32 v86, v132, v8
	v_sub_f32_e32 v9, v135, v8
	v_sub_f32_e32 v8, v134, v8
	v_mov_b32_e32 v80, v11
	v_mov_b32_e32 v81, v11
	s_waitcnt lgkmcnt(0)
	v_cvt_pk_bf16_f32 v16, v16, v17
	v_cvt_pk_bf16_f32 v17, v18, v19
	v_cvt_pk_bf16_f32 v14, v14, v15
	v_cvt_pk_bf16_f32 v12, v12, v13
	v_cndmask_b32_e64 v19, v73, v57, s[8:9]
	v_cndmask_b32_e64 v18, v72, v56, s[8:9]
	v_pk_fma_f32 v[76:77], v[76:77], v[46:47], v[50:51]
	v_sub_f32_e32 v27, v27, v10
	v_sub_f32_e32 v26, v26, v10
	v_pk_mul_f32 v[8:9], v[82:83], v[8:9]
	ds_write_b16 v157, v16
	ds_write_b16_d16_hi v157, v16 offset:104
	ds_write_b16 v157, v17 offset:208
	ds_write_b16_d16_hi v157, v17 offset:312
	ds_write_b16 v157, v14 offset:416
	ds_write_b16_d16_hi v157, v14 offset:520
	ds_write_b16 v157, v12 offset:624
	ds_write_b16_d16_hi v157, v12 offset:728
	v_cndmask_b32_e64 v13, v69, v61, s[8:9]
	v_cndmask_b32_e64 v12, v68, v60, s[8:9]
	v_cndmask_b32_e64 v17, v75, v59, s[8:9]
	v_cndmask_b32_e64 v16, v74, v58, s[8:9]
	v_sub_f32_e32 v77, v77, v10
	v_sub_f32_e32 v76, v76, v10
	v_pk_mul_f32 v[26:27], v[80:81], v[26:27]
	v_mov_b32_e32 v84, v11
	v_mov_b32_e32 v85, v11
	v_pk_add_f32 v[18:19], v[18:19], 1.0 op_sel_hi:[1,0]
	v_pk_mul_f32 v[78:79], v[78:79], v[86:87]
	v_pk_fma_f32 v[8:9], v[8:9], v[30:31], v[34:35]
	v_cndmask_b32_e64 v15, v71, v63, s[8:9]
	v_cndmask_b32_e64 v14, v70, v62, s[8:9]
	v_pk_mul_f32 v[76:77], v[84:85], v[76:77]
	v_pk_add_f32 v[16:17], v[16:17], 1.0 op_sel_hi:[1,0]
	v_pk_fma_f32 v[12:13], v[26:27], v[18:19], v[12:13]
	v_cndmask_b32_e64 v27, v67, v43, s[8:9]
	v_cndmask_b32_e64 v26, v66, v42, s[8:9]
	v_pk_fma_f32 v[78:79], v[78:79], v[28:29], v[32:33]
	v_sub_f32_e32 v9, v9, v10
	v_sub_f32_e32 v8, v8, v10
	v_pk_fma_f32 v[14:15], v[76:77], v[16:17], v[14:15]
	v_cndmask_b32_e64 v19, v55, v39, s[8:9]
	v_cndmask_b32_e64 v18, v54, v38, s[8:9]
	v_cndmask_b32_e64 v77, v65, v41, s[8:9]
	v_cndmask_b32_e64 v76, v64, v40, s[8:9]
	v_sub_f32_e32 v11, v79, v10
	v_sub_f32_e32 v10, v78, v10
	v_pk_mul_f32 v[8:9], v[84:85], v[8:9]
	v_pk_add_f32 v[26:27], v[26:27], 1.0 op_sel_hi:[1,0]
	v_cndmask_b32_e64 v17, v53, v37, s[8:9]
	v_cndmask_b32_e64 v16, v52, v36, s[8:9]
	v_pk_mul_f32 v[10:11], v[80:81], v[10:11]
	v_pk_add_f32 v[76:77], v[76:77], 1.0 op_sel_hi:[1,0]
	v_pk_fma_f32 v[8:9], v[8:9], v[26:27], v[18:19]
	v_sub_f32_e32 v19, v149, v4
	v_sub_f32_e32 v18, v148, v4
	v_mov_b32_e32 v26, v5
	v_mov_b32_e32 v27, v5
	v_mov_b32_e32 v20, v5
	v_mov_b32_e32 v21, v5
	v_pk_fma_f32 v[10:11], v[10:11], v[76:77], v[16:17]
	v_sub_f32_e32 v17, v147, v4
	v_sub_f32_e32 v16, v146, v4
	v_pk_mul_f32 v[18:19], v[26:27], v[18:19]
	v_cvt_pk_bf16_f32 v12, v12, v13
	v_cvt_pk_bf16_f32 v13, v14, v15
	v_pk_mul_f32 v[16:17], v[20:21], v[16:17]
	v_pk_fma_f32 v[18:19], v[18:19], v[46:47], v[50:51]
	v_cvt_pk_bf16_f32 v10, v10, v11
	v_cvt_pk_bf16_f32 v8, v8, v9
	ds_write_b16 v160, v12 offset:32
	ds_write_b16_d16_hi v160, v12 offset:136
	ds_write_b16 v160, v13 offset:240
	ds_write_b16_d16_hi v160, v13 offset:344
	ds_write_b16 v160, v10 offset:448
	ds_write_b16_d16_hi v160, v10 offset:552
	ds_write_b16 v160, v8 offset:656
	ds_write_b16_d16_hi v160, v8 offset:760
	v_cndmask_b32_e64 v13, v75, v59, s[10:11]
	v_cndmask_b32_e64 v12, v74, v58, s[10:11]
	v_pk_fma_f32 v[16:17], v[16:17], v[44:45], v[48:49]
	v_sub_f32_e32 v19, v19, v6
	v_sub_f32_e32 v18, v18, v6
	v_mov_b32_e32 v44, v7
	v_mov_b32_e32 v45, v7
	v_cndmask_b32_e64 v11, v71, v63, s[10:11]
	v_cndmask_b32_e64 v10, v70, v62, s[10:11]
	v_pk_mul_f32 v[18:19], v[44:45], v[18:19]
	v_pk_add_f32 v[12:13], v[12:13], 1.0 op_sel_hi:[1,0]
	v_sub_f32_e32 v5, v145, v4
	v_pk_fma_f32 v[10:11], v[18:19], v[12:13], v[10:11]
	v_cndmask_b32_e64 v13, v53, v37, s[10:11]
	v_cndmask_b32_e64 v12, v52, v36, s[10:11]
	v_sub_f32_e32 v37, v143, v4
	v_sub_f32_e32 v36, v142, v4
	v_sub_f32_e32 v4, v144, v4
	v_pk_mul_f32 v[4:5], v[26:27], v[4:5]
	v_pk_mul_f32 v[20:21], v[20:21], v[36:37]
	v_mov_b32_e32 v0, v7
	v_mov_b32_e32 v1, v7
	v_cndmask_b32_e64 v15, v73, v57, s[10:11]
	v_cndmask_b32_e64 v14, v72, v56, s[10:11]
	v_sub_f32_e32 v17, v17, v6
	v_sub_f32_e32 v16, v16, v6
	v_pk_fma_f32 v[20:21], v[20:21], v[28:29], v[32:33]
	v_pk_fma_f32 v[4:5], v[4:5], v[30:31], v[34:35]
	v_cndmask_b32_e64 v9, v69, v61, s[10:11]
	v_cndmask_b32_e64 v8, v68, v60, s[10:11]
	v_pk_mul_f32 v[16:17], v[0:1], v[16:17]
	v_pk_add_f32 v[14:15], v[14:15], 1.0 op_sel_hi:[1,0]
	v_cndmask_b32_e64 v19, v65, v41, s[10:11]
	v_cndmask_b32_e64 v18, v64, v40, s[10:11]
	v_sub_f32_e32 v5, v5, v6
	v_sub_f32_e32 v4, v4, v6
	v_sub_f32_e32 v7, v21, v6
	v_sub_f32_e32 v6, v20, v6
	v_pk_fma_f32 v[8:9], v[16:17], v[14:15], v[8:9]
	v_cndmask_b32_e64 v17, v67, v43, s[10:11]
	v_cndmask_b32_e64 v16, v66, v42, s[10:11]
	v_pk_mul_f32 v[0:1], v[0:1], v[6:7]
	v_pk_add_f32 v[6:7], v[18:19], 1.0 op_sel_hi:[1,0]
	v_cndmask_b32_e64 v15, v55, v39, s[10:11]
	v_cndmask_b32_e64 v14, v54, v38, s[10:11]
	v_pk_mul_f32 v[4:5], v[44:45], v[4:5]
	v_pk_add_f32 v[16:17], v[16:17], 1.0 op_sel_hi:[1,0]
	v_pk_fma_f32 v[0:1], v[0:1], v[6:7], v[12:13]
	v_cvt_pk_bf16_f32 v6, v8, v9
	v_pk_fma_f32 v[4:5], v[4:5], v[16:17], v[14:15]
	v_cvt_pk_bf16_f32 v7, v10, v11
	v_cvt_pk_bf16_f32 v0, v0, v1
	s_nop 0
	v_cvt_pk_bf16_f32 v1, v4, v5
	ds_write_b16 v161, v6 offset:64
	ds_write_b16_d16_hi v161, v6 offset:168
	ds_write_b16 v161, v7 offset:272
	ds_write_b16_d16_hi v161, v7 offset:376
	ds_write_b16 v161, v0 offset:480
	ds_write_b16_d16_hi v161, v0 offset:584
	ds_write_b16 v161, v1 offset:688
	ds_write_b16_d16_hi v161, v1 offset:792
	s_waitcnt lgkmcnt(0)
	ds_read2_b64 v[8:11], v117 offset1:1
	s_and_saveexec_b64 s[0:1], s[22:23]
	s_xor_b64 s[0:1], exec, s[0:1]
	v_add_lshl_u32 v0, v177, v22, 8
	v_or3_b32 v0, v0, v176, v2
	s_andn2_saveexec_b64 s[0:1], s[0:1]
	v_and_b32_e32 v0, 0xffc00, v182
	v_add_u32_e32 v0, v0, v22
	v_lshl_or_b32 v0, v0, 12, v183
	v_add_u32_e32 v0, 0x400000, v0
	s_or_b64 exec, exec, s[0:1]
	ds_read2_b64 v[4:7], v152 offset1:1
	v_lshlrev_b32_e32 v0, 1, v0
	s_waitcnt lgkmcnt(1)
	global_store_dwordx4 v0, v[8:11], s[60:61]
	s_and_saveexec_b64 s[0:1], s[14:15]
	s_xor_b64 s[0:1], exec, s[0:1]
	v_add_lshl_u32 v0, v165, v23, 8
	v_or3_b32 v0, v0, v163, v2
	s_andn2_saveexec_b64 s[0:1], s[0:1]
	v_and_b32_e32 v0, 0xffc00, v175
	v_add_u32_e32 v0, v0, v23
	v_lshl_or_b32 v0, v0, 12, v179
	v_add_u32_e32 v0, 0x400000, v0
	s_or_b64 exec, exec, s[0:1]
	ds_read2_b64 v[8:11], v153 offset1:1
	v_lshlrev_b32_e32 v0, 1, v0
	s_waitcnt lgkmcnt(1)
	global_store_dwordx4 v0, v[4:7], s[60:61]
	s_and_saveexec_b64 s[0:1], s[12:13]
	s_xor_b64 s[0:1], exec, s[0:1]
	v_add_lshl_u32 v0, v159, v24, 8
	v_or3_b32 v0, v0, v158, v2
	s_andn2_saveexec_b64 s[0:1], s[0:1]
	v_and_b32_e32 v0, 0xffc00, v162
	v_add_u32_e32 v0, v0, v24
	v_lshl_or_b32 v0, v0, 12, v166
	v_add_u32_e32 v0, 0x400000, v0
	s_or_b64 exec, exec, s[0:1]
	v_lshlrev_b32_e32 v0, 1, v0
	s_waitcnt lgkmcnt(0)
	global_store_dwordx4 v0, v[8:11], s[60:61]
	s_waitcnt lgkmcnt(0)
	s_and_b64 vcc, exec, s[2:3]
	s_mov_b64 s[0:1], -1
	s_cbranch_vccnz .LBB0_2438
	v_readlane_b32 s0, v254, 21
	v_readlane_b32 s1, v254, 22
	s_andn2_b64 vcc, exec, s[0:1]
	s_cbranch_vccnz .LBB0_2437
	s_barrier
	s_branch .LBB0_2437

.LBB0_2572:
	global_load_dword v129, v128, s[2:3] sc1
	s_waitcnt vmcnt(0)
	v_readfirstlane_b32 s4, v129
	s_cmp_gt_u32 s4, 7
	s_mov_b64 s[4:5], -1
	s_cbranch_scc1 .LBB0_2571
	s_add_i32 s1, s1, -1
	s_cmp_eq_u32 s1, 0
	s_cselect_b64 s[4:5], -1, 0
	s_sleep 1
	s_branch .LBB0_2571
